# k11b
# speedup vs baseline: 1.1105x; 1.0275x over previous
.LBB0_28:
	s_andn2_b64 vcc, exec, s[0:1]
	s_cbranch_vccnz .LBB0_45
	v_readlane_b32 s4, v254, 42
	v_readlane_b32 s5, v254, 43
	s_mov_b32 s0, s35
	s_andn2_b64 vcc, exec, s[4:5]
	s_cbranch_vccnz .LBB0_45
	s_mov_b64 s[82:83], exec
	v_readlane_b32 s4, v254, 40
	v_readlane_b32 s5, v254, 41
	v_readlane_b32 s6, v255, 15
	v_readlane_b32 s7, v254, 21
	v_readlane_b32 s9, v255, 48
	v_readlane_b32 s10, v254, 34
	v_readlane_b32 s11, v254, 35
	s_nop 4
	s_load_dword s8, s[4:5], 0x0
	v_mbcnt_lo_u32_b32 v0, -1, 0
	v_mbcnt_hi_u32_b32 v0, -1, v0
	v_and_b32_e32 v1, 31, v0
	v_lshrrev_b32_e32 v2, 5, v0
	v_or_b32_e32 v3, s7, v0
	s_lshr_b32 s7, s7, 6
	s_and_b32 s9, s9, 0xff
	s_sub_u32 s9, s9, 2
	s_cmp_eq_u32 s9, 0
	s_mov_b32 s12, 0x3f077f5a
	s_mov_b32 s13, 0x3ee34c56
	s_cselect_b32 s12, s12, s13
	v_mul_u32_u24_e32 v4, 0x110, v1
	v_lshl_add_u32 v4, v2, 4, v4
	v_mul_u32_u24_e32 v5, 0x90, v1
	v_lshl_add_u32 v5, v2, 3, v5
	v_add_u32_e32 v5, 0x4400, v5
	v_lshrrev_b32_e32 v28, 4, v3
	v_and_b32_e32 v29, 15, v3
	v_lshlrev_b32_e32 v8, 11, v28
	v_lshl_add_u32 v8, v29, 4, v8
	v_add_u32_e32 v9, 0x8000, v8
	v_add_u32_e32 v10, 0x10000, v8
	v_add_u32_e32 v11, 0x18000, v8
	v_mul_u32_u24_e32 v16, 0x110, v28
	v_lshl_add_u32 v16, v29, 4, v16
	v_lshrrev_b32_e32 v28, 3, v3
	v_and_b32_e32 v29, 7, v3
	v_lshlrev_b32_e32 v12, 12, v28
	v_lshl_add_u32 v12, v29, 4, v12
	v_add_u32_e32 v13, 0x20000, v12
	v_add_u32_e32 v14, 0x40000, v12
	v_add_u32_e32 v15, 0x60000, v12
	v_mul_u32_u24_e32 v18, 0x90, v28
	v_lshl_add_u32 v18, v29, 4, v18
	v_add_u32_e32 v18, 0x4400, v18
	v_lshlrev_b32_e32 v26, 2, v0
	v_xor_b32_e32 v26, 0x80, v26
	v_mov_b32_e32 v27, 0xf149f2ca
	s_lshl_b32 s13, s7, 5
	v_add_u32_e32 v30, s13, v1
	v_lshlrev_b32_e32 v31, 11, v30
	v_lshl_add_u32 v31, v2, 4, v31
	s_lshl_b32 s13, s9, 9
	s_add_u32 s10, s10, s13
	s_addc_u32 s11, s11, 0
	v_lshlrev_b32_e32 v28, 4, v2
	global_load_dwordx4 a[128:131], v28, s[10:11] offset:0
	global_load_dwordx4 a[132:135], v28, s[10:11] offset:32
	global_load_dwordx4 a[136:139], v28, s[10:11] offset:64
	global_load_dwordx4 a[140:143], v28, s[10:11] offset:96
	global_load_dwordx4 a[144:147], v28, s[10:11] offset:128
	global_load_dwordx4 a[148:151], v28, s[10:11] offset:160
	global_load_dwordx4 a[152:155], v28, s[10:11] offset:192
	global_load_dwordx4 a[156:159], v28, s[10:11] offset:224
	global_load_dwordx4 a[160:163], v28, s[10:11] offset:256
	global_load_dwordx4 a[164:167], v28, s[10:11] offset:288
	global_load_dwordx4 a[168:171], v28, s[10:11] offset:320
	global_load_dwordx4 a[172:175], v28, s[10:11] offset:352
	global_load_dwordx4 a[176:179], v28, s[10:11] offset:384
	global_load_dwordx4 a[180:183], v28, s[10:11] offset:416
	global_load_dwordx4 a[184:187], v28, s[10:11] offset:448
	global_load_dwordx4 a[188:191], v28, s[10:11] offset:480
	s_lshl_b32 s13, s9, 2
	s_add_u32 s14, s92, s13
	s_addc_u32 s15, s93, 0
	v_mov_b32_e32 v28, 0x4020000
	global_load_dword v24, v28, s[14:15]
	s_waitcnt lgkmcnt(0)
	s_mov_b32 s22, s6
	s_cmp_ge_u32 s22, 0x800
	s_cbranch_scc1 .Lat_done
.Lat_item:
	s_lshr_b32 s13, s22, 7
	s_sub_u32 s13, 15, s13
	s_and_b32 s14, s22, 0x7f
	s_lshr_b32 s15, s14, 3
	s_and_b32 s14, s14, 7
	s_lshl_b32 s16, s13, 7
	s_lshl_b32 s17, s13, 1
	s_add_u32 s17, s17, 2
	s_lshl_b32 s19, s15, 11
	s_add_u32 s19, s19, s16
	s_lshl_b32 s20, s19, 11
	s_lshl_b32 s21, s14, 8
	s_add_u32 s20, s20, s21
	s_add_u32 s76, s92, 0x16100000
	s_addc_u32 s77, s93, 0
	s_add_u32 s76, s76, s20
	s_addc_u32 s77, s77, 0
	global_load_dwordx4 a[0:3], v31, s[76:77] offset:0
	global_load_dwordx4 a[4:7], v31, s[76:77] offset:32
	global_load_dwordx4 a[8:11], v31, s[76:77] offset:64
	global_load_dwordx4 a[12:15], v31, s[76:77] offset:96
	global_load_dwordx4 a[16:19], v31, s[76:77] offset:128
	global_load_dwordx4 a[20:23], v31, s[76:77] offset:160
	global_load_dwordx4 a[24:27], v31, s[76:77] offset:192
	global_load_dwordx4 a[28:31], v31, s[76:77] offset:224
	s_lshl_b32 s20, s15, 22
	s_add_u32 s20, s20, s21
	s_add_u32 s78, s92, 0x1a100000
	s_addc_u32 s79, s93, 0
	s_add_u32 s78, s78, s20
	s_addc_u32 s79, s79, 0
	s_lshl_b32 s20, s15, 3
	s_add_u32 s20, s20, s14
	s_lshl_b32 s20, s20, 19
	s_add_u32 s80, s92, 0x1e100000
	s_addc_u32 s81, s93, 0
	s_add_u32 s80, s80, s20
	s_addc_u32 s81, s81, 0
	global_load_dwordx4 v[32:35], v8, s[78:79]
	global_load_dwordx4 v[36:39], v9, s[78:79]
	global_load_dwordx4 v[40:43], v10, s[78:79]
	global_load_dwordx4 v[44:47], v11, s[78:79]
	global_load_dwordx4 v[48:51], v12, s[80:81]
	global_load_dwordx4 v[52:55], v13, s[80:81]
	global_load_dwordx4 v[56:59], v14, s[80:81]
	global_load_dwordx4 v[60:63], v15, s[80:81]
	v_mov_b32_e32 v64, 0
	v_mov_b32_e32 v65, 0
	v_mov_b32_e32 v66, 0
	v_mov_b32_e32 v67, 0
	v_mov_b32_e32 v68, 0
	v_mov_b32_e32 v69, 0
	v_mov_b32_e32 v70, 0
	v_mov_b32_e32 v71, 0
	v_mov_b32_e32 v72, 0
	v_mov_b32_e32 v73, 0
	v_mov_b32_e32 v74, 0
	v_mov_b32_e32 v75, 0
	v_mov_b32_e32 v76, 0
	v_mov_b32_e32 v77, 0
	v_mov_b32_e32 v78, 0
	v_mov_b32_e32 v79, 0
	v_mov_b32_e32 v80, 0
	v_mov_b32_e32 v81, 0
	v_mov_b32_e32 v82, 0
	v_mov_b32_e32 v83, 0
	v_mov_b32_e32 v84, 0
	v_mov_b32_e32 v85, 0
	v_mov_b32_e32 v86, 0
	v_mov_b32_e32 v87, 0
	v_mov_b32_e32 v88, 0
	v_mov_b32_e32 v89, 0
	v_mov_b32_e32 v90, 0
	v_mov_b32_e32 v91, 0
	v_mov_b32_e32 v92, 0
	v_mov_b32_e32 v93, 0
	v_mov_b32_e32 v94, 0
	v_mov_b32_e32 v95, 0
	v_mov_b32_e32 v96, 0
	v_mov_b32_e32 v97, 0
	v_mov_b32_e32 v98, 0
	v_mov_b32_e32 v99, 0
	v_mov_b32_e32 v100, 0
	v_mov_b32_e32 v101, 0
	v_mov_b32_e32 v102, 0
	v_mov_b32_e32 v103, 0
	v_mov_b32_e32 v104, 0
	v_mov_b32_e32 v105, 0
	v_mov_b32_e32 v106, 0
	v_mov_b32_e32 v107, 0
	v_mov_b32_e32 v108, 0
	v_mov_b32_e32 v109, 0
	v_mov_b32_e32 v110, 0
	v_mov_b32_e32 v111, 0
	v_mov_b32_e32 v112, 0
	v_mov_b32_e32 v113, 0
	v_mov_b32_e32 v114, 0
	v_mov_b32_e32 v115, 0
	v_mov_b32_e32 v116, 0
	v_mov_b32_e32 v117, 0
	v_mov_b32_e32 v118, 0
	v_mov_b32_e32 v119, 0
	v_mov_b32_e32 v120, 0
	v_mov_b32_e32 v121, 0
	v_mov_b32_e32 v122, 0
	v_mov_b32_e32 v123, 0
	v_mov_b32_e32 v124, 0
	v_mov_b32_e32 v125, 0
	v_mov_b32_e32 v126, 0
	v_mov_b32_e32 v127, 0
	v_mov_b32_e32 v128, 0
	v_mov_b32_e32 v129, 0
	v_mov_b32_e32 v130, 0
	v_mov_b32_e32 v131, 0
	v_mov_b32_e32 v132, 0
	v_mov_b32_e32 v133, 0
	v_mov_b32_e32 v134, 0
	v_mov_b32_e32 v135, 0
	v_mov_b32_e32 v136, 0
	v_mov_b32_e32 v137, 0
	v_mov_b32_e32 v138, 0
	v_mov_b32_e32 v139, 0
	v_mov_b32_e32 v140, 0
	v_mov_b32_e32 v141, 0
	v_mov_b32_e32 v142, 0
	v_mov_b32_e32 v143, 0
	v_mov_b32_e32 v144, 0
	v_mov_b32_e32 v145, 0
	v_mov_b32_e32 v146, 0
	v_mov_b32_e32 v147, 0
	v_mov_b32_e32 v148, 0
	v_mov_b32_e32 v149, 0
	v_mov_b32_e32 v150, 0
	v_mov_b32_e32 v151, 0
	v_mov_b32_e32 v152, 0
	v_mov_b32_e32 v153, 0
	v_mov_b32_e32 v154, 0
	v_mov_b32_e32 v155, 0
	v_mov_b32_e32 v156, 0
	v_mov_b32_e32 v157, 0
	v_mov_b32_e32 v158, 0
	v_mov_b32_e32 v159, 0
	v_mov_b32_e32 v160, 0
	v_mov_b32_e32 v161, 0
	v_mov_b32_e32 v162, 0
	v_mov_b32_e32 v163, 0
	v_mov_b32_e32 v164, 0
	v_mov_b32_e32 v165, 0
	v_mov_b32_e32 v166, 0
	v_mov_b32_e32 v167, 0
	v_mov_b32_e32 v168, 0
	v_mov_b32_e32 v169, 0
	v_mov_b32_e32 v170, 0
	v_mov_b32_e32 v171, 0
	v_mov_b32_e32 v172, 0
	v_mov_b32_e32 v173, 0
	v_mov_b32_e32 v174, 0
	v_mov_b32_e32 v175, 0
	v_mov_b32_e32 v176, 0
	v_mov_b32_e32 v177, 0
	v_mov_b32_e32 v178, 0
	v_mov_b32_e32 v179, 0
	v_mov_b32_e32 v180, 0
	v_mov_b32_e32 v181, 0
	v_mov_b32_e32 v182, 0
	v_mov_b32_e32 v183, 0
	v_mov_b32_e32 v184, 0
	v_mov_b32_e32 v185, 0
	v_mov_b32_e32 v186, 0
	v_mov_b32_e32 v187, 0
	v_mov_b32_e32 v188, 0
	v_mov_b32_e32 v189, 0
	v_mov_b32_e32 v190, 0
	v_mov_b32_e32 v191, 0
	v_mov_b32_e32 v20, v27
	v_mov_b32_e32 v21, v27
	v_mov_b32_e32 v22, 0
	v_mov_b32_e32 v23, 0
	v_add_u32_e32 v25, s16, v30
	v_lshlrev_b32_e32 v28, 2, v2
	v_sub_u32_e32 v25, v25, v28
	s_lshl_b32 s84, s7, 5
	s_add_u32 s84, s84, s16
	s_mov_b32 s85, 0
	s_mov_b32 s86, 0
	s_mov_b32 s87, 0
	s_barrier
	s_waitcnt vmcnt(0)
	ds_write_b128 v16, v[32:35] offset:0
	ds_write_b128 v16, v[36:39] offset:4352
	ds_write_b128 v16, v[40:43] offset:8704
	ds_write_b128 v16, v[44:47] offset:13056
	ds_write_b128 v18, v[48:51] offset:0
	ds_write_b128 v18, v[52:55] offset:4608
	ds_write_b128 v18, v[56:59] offset:9216
	ds_write_b128 v18, v[60:63] offset:13824
	s_waitcnt lgkmcnt(0)
	s_barrier
.Lat_kb:
	s_add_u32 s88, s86, 1
	s_sub_u32 s89, s17, 1
	s_min_u32 s88, s88, s89
	s_lshl_b32 s89, s88, 17
	s_add_u32 s90, s78, s89
	s_addc_u32 s91, s79, 0
	global_load_dwordx4 v[32:35], v8, s[90:91]
	global_load_dwordx4 v[36:39], v9, s[90:91]
	global_load_dwordx4 v[40:43], v10, s[90:91]
	global_load_dwordx4 v[44:47], v11, s[90:91]
	s_lshl_b32 s89, s88, 7
	s_add_u32 s90, s80, s89
	s_addc_u32 s91, s81, 0
	global_load_dwordx4 v[48:51], v12, s[90:91]
	global_load_dwordx4 v[52:55], v13, s[90:91]
	global_load_dwordx4 v[56:59], v14, s[90:91]
	global_load_dwordx4 v[60:63], v15, s[90:91]
	s_add_u32 s88, s84, 31
	s_cmp_gt_u32 s85, s88
	s_cbranch_scc1 .Lat_skip
	v_add_u32_e32 v6, s87, v4
	v_add_u32_e32 v7, s87, v5
	ds_read2_b64 a[64:67], v7 offset0:0 offset1:2
	ds_read2_b64 a[68:71], v7 offset0:4 offset1:6
	ds_read2_b64 a[96:99], v7 offset0:8 offset1:10
	ds_read2_b64 a[100:103], v7 offset0:12 offset1:14
	v_add_u32_e32 v28, 0x1200, v7
	ds_read2_b64 a[72:75], v28 offset0:0 offset1:2
	ds_read2_b64 a[76:79], v28 offset0:4 offset1:6
	ds_read2_b64 a[104:107], v28 offset0:8 offset1:10
	ds_read2_b64 a[108:111], v28 offset0:12 offset1:14
	v_add_u32_e32 v28, 0x2400, v7
	ds_read2_b64 a[80:83], v28 offset0:0 offset1:2
	ds_read2_b64 a[84:87], v28 offset0:4 offset1:6
	ds_read2_b64 a[112:115], v28 offset0:8 offset1:10
	ds_read2_b64 a[116:119], v28 offset0:12 offset1:14
	v_add_u32_e32 v28, 0x3600, v7
	ds_read2_b64 a[88:91], v28 offset0:0 offset1:2
	ds_read2_b64 a[92:95], v28 offset0:4 offset1:6
	ds_read2_b64 a[120:123], v28 offset0:8 offset1:10
	ds_read2_b64 a[124:127], v28 offset0:12 offset1:14
	ds_read_b128 a[32:35], v6 offset:0
	ds_read_b128 a[36:39], v6 offset:32
	ds_read_b128 a[40:43], v6 offset:64
	ds_read_b128 a[44:47], v6 offset:96
	ds_read_b128 a[48:51], v6 offset:8704
	ds_read_b128 a[52:55], v6 offset:8736
	ds_read_b128 a[56:59], v6 offset:8768
	ds_read_b128 a[60:63], v6 offset:8800
	s_waitcnt lgkmcnt(7)
	v_mfma_f32_32x32x16_bf16 v[192:207], a[32:35], a[0:3], 0
	s_waitcnt lgkmcnt(3)
	v_mfma_f32_32x32x16_bf16 v[208:223], a[48:51], a[0:3], 0
	s_waitcnt lgkmcnt(6)
	v_mfma_f32_32x32x16_bf16 v[192:207], a[36:39], a[4:7], v[192:207]
	s_waitcnt lgkmcnt(2)
	v_mfma_f32_32x32x16_bf16 v[208:223], a[52:55], a[4:7], v[208:223]
	s_waitcnt lgkmcnt(5)
	v_mfma_f32_32x32x16_bf16 v[192:207], a[40:43], a[8:11], v[192:207]
	s_waitcnt lgkmcnt(1)
	v_mfma_f32_32x32x16_bf16 v[208:223], a[56:59], a[8:11], v[208:223]
	s_waitcnt lgkmcnt(4)
	v_mfma_f32_32x32x16_bf16 v[192:207], a[44:47], a[12:15], v[192:207]
	s_waitcnt lgkmcnt(0)
	v_mfma_f32_32x32x16_bf16 v[208:223], a[60:63], a[12:15], v[208:223]
	s_nop 15
	s_nop 1
	s_add_u32 s88, s85, 63
	s_cmp_gt_u32 s88, s84
	s_cbranch_scc0 .Lat_nomask_0
	v_cmp_gt_i32_e64 s[0:1], 0, v25
	v_cmp_gt_i32_e64 s[4:5], 1, v25
	v_cmp_gt_i32_e64 s[10:11], 2, v25
	v_cmp_gt_i32_e64 s[20:21], 3, v25
	v_cndmask_b32_e64 v192, v192, v27, s[0:1]
	v_cndmask_b32_e64 v193, v193, v27, s[4:5]
	v_cndmask_b32_e64 v194, v194, v27, s[10:11]
	v_cndmask_b32_e64 v195, v195, v27, s[20:21]
	v_cmp_gt_i32_e64 s[0:1], 8, v25
	v_cmp_gt_i32_e64 s[4:5], 9, v25
	v_cmp_gt_i32_e64 s[10:11], 10, v25
	v_cmp_gt_i32_e64 s[20:21], 11, v25
	v_cndmask_b32_e64 v196, v196, v27, s[0:1]
	v_cndmask_b32_e64 v197, v197, v27, s[4:5]
	v_cndmask_b32_e64 v198, v198, v27, s[10:11]
	v_cndmask_b32_e64 v199, v199, v27, s[20:21]
	v_cmp_gt_i32_e64 s[0:1], 16, v25
	v_cmp_gt_i32_e64 s[4:5], 17, v25
	v_cmp_gt_i32_e64 s[10:11], 18, v25
	v_cmp_gt_i32_e64 s[20:21], 19, v25
	v_cndmask_b32_e64 v200, v200, v27, s[0:1]
	v_cndmask_b32_e64 v201, v201, v27, s[4:5]
	v_cndmask_b32_e64 v202, v202, v27, s[10:11]
	v_cndmask_b32_e64 v203, v203, v27, s[20:21]
	v_cmp_gt_i32_e64 s[0:1], 24, v25
	v_cmp_gt_i32_e64 s[4:5], 25, v25
	v_cmp_gt_i32_e64 s[10:11], 26, v25
	v_cmp_gt_i32_e64 s[20:21], 27, v25
	v_cndmask_b32_e64 v204, v204, v27, s[0:1]
	v_cndmask_b32_e64 v205, v205, v27, s[4:5]
	v_cndmask_b32_e64 v206, v206, v27, s[10:11]
	v_cndmask_b32_e64 v207, v207, v27, s[20:21]
	v_cmp_gt_i32_e64 s[0:1], 32, v25
	v_cmp_gt_i32_e64 s[4:5], 33, v25
	v_cmp_gt_i32_e64 s[10:11], 34, v25
	v_cmp_gt_i32_e64 s[20:21], 35, v25
	v_cndmask_b32_e64 v208, v208, v27, s[0:1]
	v_cndmask_b32_e64 v209, v209, v27, s[4:5]
	v_cndmask_b32_e64 v210, v210, v27, s[10:11]
	v_cndmask_b32_e64 v211, v211, v27, s[20:21]
	v_cmp_gt_i32_e64 s[0:1], 40, v25
	v_cmp_gt_i32_e64 s[4:5], 41, v25
	v_cmp_gt_i32_e64 s[10:11], 42, v25
	v_cmp_gt_i32_e64 s[20:21], 43, v25
	v_cndmask_b32_e64 v212, v212, v27, s[0:1]
	v_cndmask_b32_e64 v213, v213, v27, s[4:5]
	v_cndmask_b32_e64 v214, v214, v27, s[10:11]
	v_cndmask_b32_e64 v215, v215, v27, s[20:21]
	v_cmp_gt_i32_e64 s[0:1], 48, v25
	v_cmp_gt_i32_e64 s[4:5], 49, v25
	v_cmp_gt_i32_e64 s[10:11], 50, v25
	v_cmp_gt_i32_e64 s[20:21], 51, v25
	v_cndmask_b32_e64 v216, v216, v27, s[0:1]
	v_cndmask_b32_e64 v217, v217, v27, s[4:5]
	v_cndmask_b32_e64 v218, v218, v27, s[10:11]
	v_cndmask_b32_e64 v219, v219, v27, s[20:21]
	v_cmp_gt_i32_e64 s[0:1], 56, v25
	v_cmp_gt_i32_e64 s[4:5], 57, v25
	v_cmp_gt_i32_e64 s[10:11], 58, v25
	v_cmp_gt_i32_e64 s[20:21], 59, v25
	v_cndmask_b32_e64 v220, v220, v27, s[0:1]
	v_cndmask_b32_e64 v221, v221, v27, s[4:5]
	v_cndmask_b32_e64 v222, v222, v27, s[10:11]
	v_cndmask_b32_e64 v223, v223, v27, s[20:21]
.Lat_nomask_0:
	v_max3_f32 v232, v192, v193, v194
	v_max3_f32 v232, v232, v195, v196
	v_max3_f32 v232, v232, v197, v198
	v_max3_f32 v232, v232, v199, v200
	v_max3_f32 v232, v232, v201, v202
	v_max3_f32 v232, v232, v203, v204
	v_max3_f32 v232, v232, v205, v206
	v_max3_f32 v232, v232, v207, v208
	v_max3_f32 v232, v232, v209, v210
	v_max3_f32 v232, v232, v211, v212
	v_max3_f32 v232, v232, v213, v214
	v_max3_f32 v232, v232, v215, v216
	v_max3_f32 v232, v232, v217, v218
	v_max3_f32 v232, v232, v219, v220
	v_max3_f32 v232, v232, v221, v222
	v_max_f32_e32 v232, v232, v223
	ds_bpermute_b32 v233, v26, v232
	s_waitcnt lgkmcnt(0)
	v_max3_f32 v234, v232, v233, v20
	v_sub_f32_e32 v236, v20, v234
	v_exp_f32_e32 v236, v236
	v_mov_b32_e32 v20, v234
	v_sub_f32_e32 v192, v192, v234
	v_sub_f32_e32 v193, v193, v234
	v_sub_f32_e32 v194, v194, v234
	v_sub_f32_e32 v195, v195, v234
	v_sub_f32_e32 v196, v196, v234
	v_sub_f32_e32 v197, v197, v234
	v_sub_f32_e32 v198, v198, v234
	v_sub_f32_e32 v199, v199, v234
	v_sub_f32_e32 v200, v200, v234
	v_sub_f32_e32 v201, v201, v234
	v_sub_f32_e32 v202, v202, v234
	v_sub_f32_e32 v203, v203, v234
	v_sub_f32_e32 v204, v204, v234
	v_sub_f32_e32 v205, v205, v234
	v_sub_f32_e32 v206, v206, v234
	v_sub_f32_e32 v207, v207, v234
	v_sub_f32_e32 v208, v208, v234
	v_sub_f32_e32 v209, v209, v234
	v_sub_f32_e32 v210, v210, v234
	v_sub_f32_e32 v211, v211, v234
	v_sub_f32_e32 v212, v212, v234
	v_sub_f32_e32 v213, v213, v234
	v_sub_f32_e32 v214, v214, v234
	v_sub_f32_e32 v215, v215, v234
	v_sub_f32_e32 v216, v216, v234
	v_sub_f32_e32 v217, v217, v234
	v_sub_f32_e32 v218, v218, v234
	v_sub_f32_e32 v219, v219, v234
	v_sub_f32_e32 v220, v220, v234
	v_sub_f32_e32 v221, v221, v234
	v_sub_f32_e32 v222, v222, v234
	v_sub_f32_e32 v223, v223, v234
	v_exp_f32_e32 v192, v192
	v_exp_f32_e32 v193, v193
	v_exp_f32_e32 v194, v194
	v_exp_f32_e32 v195, v195
	v_exp_f32_e32 v196, v196
	v_exp_f32_e32 v197, v197
	v_exp_f32_e32 v198, v198
	v_exp_f32_e32 v199, v199
	v_exp_f32_e32 v200, v200
	v_exp_f32_e32 v201, v201
	v_exp_f32_e32 v202, v202
	v_exp_f32_e32 v203, v203
	v_exp_f32_e32 v204, v204
	v_exp_f32_e32 v205, v205
	v_exp_f32_e32 v206, v206
	v_exp_f32_e32 v207, v207
	v_exp_f32_e32 v208, v208
	v_exp_f32_e32 v209, v209
	v_exp_f32_e32 v210, v210
	v_exp_f32_e32 v211, v211
	v_exp_f32_e32 v212, v212
	v_exp_f32_e32 v213, v213
	v_exp_f32_e32 v214, v214
	v_exp_f32_e32 v215, v215
	v_exp_f32_e32 v216, v216
	v_exp_f32_e32 v217, v217
	v_exp_f32_e32 v218, v218
	v_exp_f32_e32 v219, v219
	v_exp_f32_e32 v220, v220
	v_exp_f32_e32 v221, v221
	v_exp_f32_e32 v222, v222
	v_exp_f32_e32 v223, v223
	v_mul_f32_e32 v22, v22, v236
	v_add_f32_e32 v238, v192, v193
	v_add_f32_e32 v238, v238, v194
	v_add_f32_e32 v238, v238, v195
	v_add_f32_e32 v238, v238, v196
	v_add_f32_e32 v238, v238, v197
	v_add_f32_e32 v238, v238, v198
	v_add_f32_e32 v238, v238, v199
	v_add_f32_e32 v238, v238, v200
	v_add_f32_e32 v238, v238, v201
	v_add_f32_e32 v238, v238, v202
	v_add_f32_e32 v238, v238, v203
	v_add_f32_e32 v238, v238, v204
	v_add_f32_e32 v238, v238, v205
	v_add_f32_e32 v238, v238, v206
	v_add_f32_e32 v238, v238, v207
	v_add_f32_e32 v238, v238, v208
	v_add_f32_e32 v238, v238, v209
	v_add_f32_e32 v238, v238, v210
	v_add_f32_e32 v238, v238, v211
	v_add_f32_e32 v238, v238, v212
	v_add_f32_e32 v238, v238, v213
	v_add_f32_e32 v238, v238, v214
	v_add_f32_e32 v238, v238, v215
	v_add_f32_e32 v238, v238, v216
	v_add_f32_e32 v238, v238, v217
	v_add_f32_e32 v238, v238, v218
	v_add_f32_e32 v238, v238, v219
	v_add_f32_e32 v238, v238, v220
	v_add_f32_e32 v238, v238, v221
	v_add_f32_e32 v238, v238, v222
	v_add_f32_e32 v238, v238, v223
	v_add_f32_e32 v22, v22, v238
	v_pk_mul_f32 v[64:65], v[64:65], v[236:237] op_sel_hi:[1,0]
	v_pk_mul_f32 v[66:67], v[66:67], v[236:237] op_sel_hi:[1,0]
	v_pk_mul_f32 v[68:69], v[68:69], v[236:237] op_sel_hi:[1,0]
	v_pk_mul_f32 v[70:71], v[70:71], v[236:237] op_sel_hi:[1,0]
	v_pk_mul_f32 v[72:73], v[72:73], v[236:237] op_sel_hi:[1,0]
	v_pk_mul_f32 v[74:75], v[74:75], v[236:237] op_sel_hi:[1,0]
	v_pk_mul_f32 v[76:77], v[76:77], v[236:237] op_sel_hi:[1,0]
	v_pk_mul_f32 v[78:79], v[78:79], v[236:237] op_sel_hi:[1,0]
	v_pk_mul_f32 v[80:81], v[80:81], v[236:237] op_sel_hi:[1,0]
	v_pk_mul_f32 v[82:83], v[82:83], v[236:237] op_sel_hi:[1,0]
	v_pk_mul_f32 v[84:85], v[84:85], v[236:237] op_sel_hi:[1,0]
	v_pk_mul_f32 v[86:87], v[86:87], v[236:237] op_sel_hi:[1,0]
	v_pk_mul_f32 v[88:89], v[88:89], v[236:237] op_sel_hi:[1,0]
	v_pk_mul_f32 v[90:91], v[90:91], v[236:237] op_sel_hi:[1,0]
	v_pk_mul_f32 v[92:93], v[92:93], v[236:237] op_sel_hi:[1,0]
	v_pk_mul_f32 v[94:95], v[94:95], v[236:237] op_sel_hi:[1,0]
	v_pk_mul_f32 v[96:97], v[96:97], v[236:237] op_sel_hi:[1,0]
	v_pk_mul_f32 v[98:99], v[98:99], v[236:237] op_sel_hi:[1,0]
	v_pk_mul_f32 v[100:101], v[100:101], v[236:237] op_sel_hi:[1,0]
	v_pk_mul_f32 v[102:103], v[102:103], v[236:237] op_sel_hi:[1,0]
	v_pk_mul_f32 v[104:105], v[104:105], v[236:237] op_sel_hi:[1,0]
	v_pk_mul_f32 v[106:107], v[106:107], v[236:237] op_sel_hi:[1,0]
	v_pk_mul_f32 v[108:109], v[108:109], v[236:237] op_sel_hi:[1,0]
	v_pk_mul_f32 v[110:111], v[110:111], v[236:237] op_sel_hi:[1,0]
	v_pk_mul_f32 v[112:113], v[112:113], v[236:237] op_sel_hi:[1,0]
	v_pk_mul_f32 v[114:115], v[114:115], v[236:237] op_sel_hi:[1,0]
	v_pk_mul_f32 v[116:117], v[116:117], v[236:237] op_sel_hi:[1,0]
	v_pk_mul_f32 v[118:119], v[118:119], v[236:237] op_sel_hi:[1,0]
	v_pk_mul_f32 v[120:121], v[120:121], v[236:237] op_sel_hi:[1,0]
	v_pk_mul_f32 v[122:123], v[122:123], v[236:237] op_sel_hi:[1,0]
	v_pk_mul_f32 v[124:125], v[124:125], v[236:237] op_sel_hi:[1,0]
	v_pk_mul_f32 v[126:127], v[126:127], v[236:237] op_sel_hi:[1,0]
	v_cvt_pk_bf16_f32 v224, v192, v193
	v_cvt_pk_bf16_f32 v225, v194, v195
	v_cvt_pk_bf16_f32 v226, v196, v197
	v_cvt_pk_bf16_f32 v227, v198, v199
	v_cvt_pk_bf16_f32 v228, v200, v201
	v_cvt_pk_bf16_f32 v229, v202, v203
	v_cvt_pk_bf16_f32 v230, v204, v205
	v_cvt_pk_bf16_f32 v231, v206, v207
	v_cvt_pk_bf16_f32 v240, v208, v209
	v_cvt_pk_bf16_f32 v241, v210, v211
	v_cvt_pk_bf16_f32 v242, v212, v213
	v_cvt_pk_bf16_f32 v243, v214, v215
	v_cvt_pk_bf16_f32 v244, v216, v217
	v_cvt_pk_bf16_f32 v245, v218, v219
	v_cvt_pk_bf16_f32 v246, v220, v221
	v_cvt_pk_bf16_f32 v247, v222, v223
	s_nop 1
	s_waitcnt lgkmcnt(0)
	v_mfma_f32_32x32x16_bf16 v[64:79], a[64:67], v[224:227], v[64:79]
	v_mfma_f32_32x32x16_bf16 v[64:79], a[68:71], v[228:231], v[64:79]
	v_mfma_f32_32x32x16_bf16 v[80:95], a[72:75], v[224:227], v[80:95]
	v_mfma_f32_32x32x16_bf16 v[80:95], a[76:79], v[228:231], v[80:95]
	v_mfma_f32_32x32x16_bf16 v[96:111], a[80:83], v[224:227], v[96:111]
	v_mfma_f32_32x32x16_bf16 v[96:111], a[84:87], v[228:231], v[96:111]
	v_mfma_f32_32x32x16_bf16 v[112:127], a[88:91], v[224:227], v[112:127]
	v_mfma_f32_32x32x16_bf16 v[112:127], a[92:95], v[228:231], v[112:127]
	v_mfma_f32_32x32x16_bf16 v[64:79], a[96:99], v[240:243], v[64:79]
	v_mfma_f32_32x32x16_bf16 v[64:79], a[100:103], v[244:247], v[64:79]
	v_mfma_f32_32x32x16_bf16 v[80:95], a[104:107], v[240:243], v[80:95]
	v_mfma_f32_32x32x16_bf16 v[80:95], a[108:111], v[244:247], v[80:95]
	v_mfma_f32_32x32x16_bf16 v[96:111], a[112:115], v[240:243], v[96:111]
	v_mfma_f32_32x32x16_bf16 v[96:111], a[116:119], v[244:247], v[96:111]
	v_mfma_f32_32x32x16_bf16 v[112:127], a[120:123], v[240:243], v[112:127]
	v_mfma_f32_32x32x16_bf16 v[112:127], a[124:127], v[244:247], v[112:127]
	ds_read_b128 a[32:35], v6 offset:128
	ds_read_b128 a[36:39], v6 offset:160
	ds_read_b128 a[40:43], v6 offset:192
	ds_read_b128 a[44:47], v6 offset:224
	ds_read_b128 a[48:51], v6 offset:8832
	ds_read_b128 a[52:55], v6 offset:8864
	ds_read_b128 a[56:59], v6 offset:8896
	ds_read_b128 a[60:63], v6 offset:8928
	s_waitcnt lgkmcnt(7)
	v_mfma_f32_32x32x16_bf16 v[192:207], a[32:35], a[16:19], 0
	s_waitcnt lgkmcnt(3)
	v_mfma_f32_32x32x16_bf16 v[208:223], a[48:51], a[16:19], 0
	s_waitcnt lgkmcnt(6)
	v_mfma_f32_32x32x16_bf16 v[192:207], a[36:39], a[20:23], v[192:207]
	s_waitcnt lgkmcnt(2)
	v_mfma_f32_32x32x16_bf16 v[208:223], a[52:55], a[20:23], v[208:223]
	s_waitcnt lgkmcnt(5)
	v_mfma_f32_32x32x16_bf16 v[192:207], a[40:43], a[24:27], v[192:207]
	s_waitcnt lgkmcnt(1)
	v_mfma_f32_32x32x16_bf16 v[208:223], a[56:59], a[24:27], v[208:223]
	s_waitcnt lgkmcnt(4)
	v_mfma_f32_32x32x16_bf16 v[192:207], a[44:47], a[28:31], v[192:207]
	s_waitcnt lgkmcnt(0)
	v_mfma_f32_32x32x16_bf16 v[208:223], a[60:63], a[28:31], v[208:223]
	s_nop 15
	s_nop 1
	s_add_u32 s88, s85, 63
	s_cmp_gt_u32 s88, s84
	s_cbranch_scc0 .Lat_nomask_1
	v_cmp_gt_i32_e64 s[0:1], 0, v25
	v_cmp_gt_i32_e64 s[4:5], 1, v25
	v_cmp_gt_i32_e64 s[10:11], 2, v25
	v_cmp_gt_i32_e64 s[20:21], 3, v25
	v_cndmask_b32_e64 v192, v192, v27, s[0:1]
	v_cndmask_b32_e64 v193, v193, v27, s[4:5]
	v_cndmask_b32_e64 v194, v194, v27, s[10:11]
	v_cndmask_b32_e64 v195, v195, v27, s[20:21]
	v_cmp_gt_i32_e64 s[0:1], 8, v25
	v_cmp_gt_i32_e64 s[4:5], 9, v25
	v_cmp_gt_i32_e64 s[10:11], 10, v25
	v_cmp_gt_i32_e64 s[20:21], 11, v25
	v_cndmask_b32_e64 v196, v196, v27, s[0:1]
	v_cndmask_b32_e64 v197, v197, v27, s[4:5]
	v_cndmask_b32_e64 v198, v198, v27, s[10:11]
	v_cndmask_b32_e64 v199, v199, v27, s[20:21]
	v_cmp_gt_i32_e64 s[0:1], 16, v25
	v_cmp_gt_i32_e64 s[4:5], 17, v25
	v_cmp_gt_i32_e64 s[10:11], 18, v25
	v_cmp_gt_i32_e64 s[20:21], 19, v25
	v_cndmask_b32_e64 v200, v200, v27, s[0:1]
	v_cndmask_b32_e64 v201, v201, v27, s[4:5]
	v_cndmask_b32_e64 v202, v202, v27, s[10:11]
	v_cndmask_b32_e64 v203, v203, v27, s[20:21]
	v_cmp_gt_i32_e64 s[0:1], 24, v25
	v_cmp_gt_i32_e64 s[4:5], 25, v25
	v_cmp_gt_i32_e64 s[10:11], 26, v25
	v_cmp_gt_i32_e64 s[20:21], 27, v25
	v_cndmask_b32_e64 v204, v204, v27, s[0:1]
	v_cndmask_b32_e64 v205, v205, v27, s[4:5]
	v_cndmask_b32_e64 v206, v206, v27, s[10:11]
	v_cndmask_b32_e64 v207, v207, v27, s[20:21]
	v_cmp_gt_i32_e64 s[0:1], 32, v25
	v_cmp_gt_i32_e64 s[4:5], 33, v25
	v_cmp_gt_i32_e64 s[10:11], 34, v25
	v_cmp_gt_i32_e64 s[20:21], 35, v25
	v_cndmask_b32_e64 v208, v208, v27, s[0:1]
	v_cndmask_b32_e64 v209, v209, v27, s[4:5]
	v_cndmask_b32_e64 v210, v210, v27, s[10:11]
	v_cndmask_b32_e64 v211, v211, v27, s[20:21]
	v_cmp_gt_i32_e64 s[0:1], 40, v25
	v_cmp_gt_i32_e64 s[4:5], 41, v25
	v_cmp_gt_i32_e64 s[10:11], 42, v25
	v_cmp_gt_i32_e64 s[20:21], 43, v25
	v_cndmask_b32_e64 v212, v212, v27, s[0:1]
	v_cndmask_b32_e64 v213, v213, v27, s[4:5]
	v_cndmask_b32_e64 v214, v214, v27, s[10:11]
	v_cndmask_b32_e64 v215, v215, v27, s[20:21]
	v_cmp_gt_i32_e64 s[0:1], 48, v25
	v_cmp_gt_i32_e64 s[4:5], 49, v25
	v_cmp_gt_i32_e64 s[10:11], 50, v25
	v_cmp_gt_i32_e64 s[20:21], 51, v25
	v_cndmask_b32_e64 v216, v216, v27, s[0:1]
	v_cndmask_b32_e64 v217, v217, v27, s[4:5]
	v_cndmask_b32_e64 v218, v218, v27, s[10:11]
	v_cndmask_b32_e64 v219, v219, v27, s[20:21]
	v_cmp_gt_i32_e64 s[0:1], 56, v25
	v_cmp_gt_i32_e64 s[4:5], 57, v25
	v_cmp_gt_i32_e64 s[10:11], 58, v25
	v_cmp_gt_i32_e64 s[20:21], 59, v25
	v_cndmask_b32_e64 v220, v220, v27, s[0:1]
	v_cndmask_b32_e64 v221, v221, v27, s[4:5]
	v_cndmask_b32_e64 v222, v222, v27, s[10:11]
	v_cndmask_b32_e64 v223, v223, v27, s[20:21]
.Lat_nomask_1:
	v_max3_f32 v232, v192, v193, v194
	v_max3_f32 v232, v232, v195, v196
	v_max3_f32 v232, v232, v197, v198
	v_max3_f32 v232, v232, v199, v200
	v_max3_f32 v232, v232, v201, v202
	v_max3_f32 v232, v232, v203, v204
	v_max3_f32 v232, v232, v205, v206
	v_max3_f32 v232, v232, v207, v208
	v_max3_f32 v232, v232, v209, v210
	v_max3_f32 v232, v232, v211, v212
	v_max3_f32 v232, v232, v213, v214
	v_max3_f32 v232, v232, v215, v216
	v_max3_f32 v232, v232, v217, v218
	v_max3_f32 v232, v232, v219, v220
	v_max3_f32 v232, v232, v221, v222
	v_max_f32_e32 v232, v232, v223
	ds_bpermute_b32 v233, v26, v232
	s_waitcnt lgkmcnt(0)
	v_max3_f32 v234, v232, v233, v21
	v_sub_f32_e32 v236, v21, v234
	v_exp_f32_e32 v236, v236
	v_mov_b32_e32 v21, v234
	v_sub_f32_e32 v192, v192, v234
	v_sub_f32_e32 v193, v193, v234
	v_sub_f32_e32 v194, v194, v234
	v_sub_f32_e32 v195, v195, v234
	v_sub_f32_e32 v196, v196, v234
	v_sub_f32_e32 v197, v197, v234
	v_sub_f32_e32 v198, v198, v234
	v_sub_f32_e32 v199, v199, v234
	v_sub_f32_e32 v200, v200, v234
	v_sub_f32_e32 v201, v201, v234
	v_sub_f32_e32 v202, v202, v234
	v_sub_f32_e32 v203, v203, v234
	v_sub_f32_e32 v204, v204, v234
	v_sub_f32_e32 v205, v205, v234
	v_sub_f32_e32 v206, v206, v234
	v_sub_f32_e32 v207, v207, v234
	v_sub_f32_e32 v208, v208, v234
	v_sub_f32_e32 v209, v209, v234
	v_sub_f32_e32 v210, v210, v234
	v_sub_f32_e32 v211, v211, v234
	v_sub_f32_e32 v212, v212, v234
	v_sub_f32_e32 v213, v213, v234
	v_sub_f32_e32 v214, v214, v234
	v_sub_f32_e32 v215, v215, v234
	v_sub_f32_e32 v216, v216, v234
	v_sub_f32_e32 v217, v217, v234
	v_sub_f32_e32 v218, v218, v234
	v_sub_f32_e32 v219, v219, v234
	v_sub_f32_e32 v220, v220, v234
	v_sub_f32_e32 v221, v221, v234
	v_sub_f32_e32 v222, v222, v234
	v_sub_f32_e32 v223, v223, v234
	v_exp_f32_e32 v192, v192
	v_exp_f32_e32 v193, v193
	v_exp_f32_e32 v194, v194
	v_exp_f32_e32 v195, v195
	v_exp_f32_e32 v196, v196
	v_exp_f32_e32 v197, v197
	v_exp_f32_e32 v198, v198
	v_exp_f32_e32 v199, v199
	v_exp_f32_e32 v200, v200
	v_exp_f32_e32 v201, v201
	v_exp_f32_e32 v202, v202
	v_exp_f32_e32 v203, v203
	v_exp_f32_e32 v204, v204
	v_exp_f32_e32 v205, v205
	v_exp_f32_e32 v206, v206
	v_exp_f32_e32 v207, v207
	v_exp_f32_e32 v208, v208
	v_exp_f32_e32 v209, v209
	v_exp_f32_e32 v210, v210
	v_exp_f32_e32 v211, v211
	v_exp_f32_e32 v212, v212
	v_exp_f32_e32 v213, v213
	v_exp_f32_e32 v214, v214
	v_exp_f32_e32 v215, v215
	v_exp_f32_e32 v216, v216
	v_exp_f32_e32 v217, v217
	v_exp_f32_e32 v218, v218
	v_exp_f32_e32 v219, v219
	v_exp_f32_e32 v220, v220
	v_exp_f32_e32 v221, v221
	v_exp_f32_e32 v222, v222
	v_exp_f32_e32 v223, v223
	v_mul_f32_e32 v23, v23, v236
	v_add_f32_e32 v238, v192, v193
	v_add_f32_e32 v238, v238, v194
	v_add_f32_e32 v238, v238, v195
	v_add_f32_e32 v238, v238, v196
	v_add_f32_e32 v238, v238, v197
	v_add_f32_e32 v238, v238, v198
	v_add_f32_e32 v238, v238, v199
	v_add_f32_e32 v238, v238, v200
	v_add_f32_e32 v238, v238, v201
	v_add_f32_e32 v238, v238, v202
	v_add_f32_e32 v238, v238, v203
	v_add_f32_e32 v238, v238, v204
	v_add_f32_e32 v238, v238, v205
	v_add_f32_e32 v238, v238, v206
	v_add_f32_e32 v238, v238, v207
	v_add_f32_e32 v238, v238, v208
	v_add_f32_e32 v238, v238, v209
	v_add_f32_e32 v238, v238, v210
	v_add_f32_e32 v238, v238, v211
	v_add_f32_e32 v238, v238, v212
	v_add_f32_e32 v238, v238, v213
	v_add_f32_e32 v238, v238, v214
	v_add_f32_e32 v238, v238, v215
	v_add_f32_e32 v238, v238, v216
	v_add_f32_e32 v238, v238, v217
	v_add_f32_e32 v238, v238, v218
	v_add_f32_e32 v238, v238, v219
	v_add_f32_e32 v238, v238, v220
	v_add_f32_e32 v238, v238, v221
	v_add_f32_e32 v238, v238, v222
	v_add_f32_e32 v238, v238, v223
	v_add_f32_e32 v23, v23, v238
	v_pk_mul_f32 v[128:129], v[128:129], v[236:237] op_sel_hi:[1,0]
	v_pk_mul_f32 v[130:131], v[130:131], v[236:237] op_sel_hi:[1,0]
	v_pk_mul_f32 v[132:133], v[132:133], v[236:237] op_sel_hi:[1,0]
	v_pk_mul_f32 v[134:135], v[134:135], v[236:237] op_sel_hi:[1,0]
	v_pk_mul_f32 v[136:137], v[136:137], v[236:237] op_sel_hi:[1,0]
	v_pk_mul_f32 v[138:139], v[138:139], v[236:237] op_sel_hi:[1,0]
	v_pk_mul_f32 v[140:141], v[140:141], v[236:237] op_sel_hi:[1,0]
	v_pk_mul_f32 v[142:143], v[142:143], v[236:237] op_sel_hi:[1,0]
	v_pk_mul_f32 v[144:145], v[144:145], v[236:237] op_sel_hi:[1,0]
	v_pk_mul_f32 v[146:147], v[146:147], v[236:237] op_sel_hi:[1,0]
	v_pk_mul_f32 v[148:149], v[148:149], v[236:237] op_sel_hi:[1,0]
	v_pk_mul_f32 v[150:151], v[150:151], v[236:237] op_sel_hi:[1,0]
	v_pk_mul_f32 v[152:153], v[152:153], v[236:237] op_sel_hi:[1,0]
	v_pk_mul_f32 v[154:155], v[154:155], v[236:237] op_sel_hi:[1,0]
	v_pk_mul_f32 v[156:157], v[156:157], v[236:237] op_sel_hi:[1,0]
	v_pk_mul_f32 v[158:159], v[158:159], v[236:237] op_sel_hi:[1,0]
	v_pk_mul_f32 v[160:161], v[160:161], v[236:237] op_sel_hi:[1,0]
	v_pk_mul_f32 v[162:163], v[162:163], v[236:237] op_sel_hi:[1,0]
	v_pk_mul_f32 v[164:165], v[164:165], v[236:237] op_sel_hi:[1,0]
	v_pk_mul_f32 v[166:167], v[166:167], v[236:237] op_sel_hi:[1,0]
	v_pk_mul_f32 v[168:169], v[168:169], v[236:237] op_sel_hi:[1,0]
	v_pk_mul_f32 v[170:171], v[170:171], v[236:237] op_sel_hi:[1,0]
	v_pk_mul_f32 v[172:173], v[172:173], v[236:237] op_sel_hi:[1,0]
	v_pk_mul_f32 v[174:175], v[174:175], v[236:237] op_sel_hi:[1,0]
	v_pk_mul_f32 v[176:177], v[176:177], v[236:237] op_sel_hi:[1,0]
	v_pk_mul_f32 v[178:179], v[178:179], v[236:237] op_sel_hi:[1,0]
	v_pk_mul_f32 v[180:181], v[180:181], v[236:237] op_sel_hi:[1,0]
	v_pk_mul_f32 v[182:183], v[182:183], v[236:237] op_sel_hi:[1,0]
	v_pk_mul_f32 v[184:185], v[184:185], v[236:237] op_sel_hi:[1,0]
	v_pk_mul_f32 v[186:187], v[186:187], v[236:237] op_sel_hi:[1,0]
	v_pk_mul_f32 v[188:189], v[188:189], v[236:237] op_sel_hi:[1,0]
	v_pk_mul_f32 v[190:191], v[190:191], v[236:237] op_sel_hi:[1,0]
	v_cvt_pk_bf16_f32 v224, v192, v193
	v_cvt_pk_bf16_f32 v225, v194, v195
	v_cvt_pk_bf16_f32 v226, v196, v197
	v_cvt_pk_bf16_f32 v227, v198, v199
	v_cvt_pk_bf16_f32 v228, v200, v201
	v_cvt_pk_bf16_f32 v229, v202, v203
	v_cvt_pk_bf16_f32 v230, v204, v205
	v_cvt_pk_bf16_f32 v231, v206, v207
	v_cvt_pk_bf16_f32 v240, v208, v209
	v_cvt_pk_bf16_f32 v241, v210, v211
	v_cvt_pk_bf16_f32 v242, v212, v213
	v_cvt_pk_bf16_f32 v243, v214, v215
	v_cvt_pk_bf16_f32 v244, v216, v217
	v_cvt_pk_bf16_f32 v245, v218, v219
	v_cvt_pk_bf16_f32 v246, v220, v221
	v_cvt_pk_bf16_f32 v247, v222, v223
	s_nop 1
	v_mfma_f32_32x32x16_bf16 v[128:143], a[64:67], v[224:227], v[128:143]
	v_mfma_f32_32x32x16_bf16 v[128:143], a[68:71], v[228:231], v[128:143]
	v_mfma_f32_32x32x16_bf16 v[144:159], a[72:75], v[224:227], v[144:159]
	v_mfma_f32_32x32x16_bf16 v[144:159], a[76:79], v[228:231], v[144:159]
	v_mfma_f32_32x32x16_bf16 v[160:175], a[80:83], v[224:227], v[160:175]
	v_mfma_f32_32x32x16_bf16 v[160:175], a[84:87], v[228:231], v[160:175]
	v_mfma_f32_32x32x16_bf16 v[176:191], a[88:91], v[224:227], v[176:191]
	v_mfma_f32_32x32x16_bf16 v[176:191], a[92:95], v[228:231], v[176:191]
	v_mfma_f32_32x32x16_bf16 v[128:143], a[96:99], v[240:243], v[128:143]
	v_mfma_f32_32x32x16_bf16 v[128:143], a[100:103], v[244:247], v[128:143]
	v_mfma_f32_32x32x16_bf16 v[144:159], a[104:107], v[240:243], v[144:159]
	v_mfma_f32_32x32x16_bf16 v[144:159], a[108:111], v[244:247], v[144:159]
	v_mfma_f32_32x32x16_bf16 v[160:175], a[112:115], v[240:243], v[160:175]
	v_mfma_f32_32x32x16_bf16 v[160:175], a[116:119], v[244:247], v[160:175]
	v_mfma_f32_32x32x16_bf16 v[176:191], a[120:123], v[240:243], v[176:191]
	v_mfma_f32_32x32x16_bf16 v[176:191], a[124:127], v[244:247], v[176:191]
.Lat_skip:
	s_xor_b32 s87, s87, 0x8c00
	v_add_u32_e32 v17, s87, v16
	v_add_u32_e32 v19, s87, v18
	s_waitcnt vmcnt(0)
	ds_write_b128 v17, v[32:35] offset:0
	ds_write_b128 v17, v[36:39] offset:4352
	ds_write_b128 v17, v[40:43] offset:8704
	ds_write_b128 v17, v[44:47] offset:13056
	ds_write_b128 v19, v[48:51] offset:0
	ds_write_b128 v19, v[52:55] offset:4608
	ds_write_b128 v19, v[56:59] offset:9216
	ds_write_b128 v19, v[60:63] offset:13824
	s_waitcnt lgkmcnt(0)
	s_barrier
	s_add_u32 s86, s86, 1
	s_add_u32 s85, s85, 64
	v_subrev_u32_e32 v25, 64, v25
	s_cmp_lt_u32 s86, s17
	s_cbranch_scc1 .Lat_kb
	s_nop 15
	ds_bpermute_b32 v232, v26, v22
	ds_bpermute_b32 v233, v26, v23
	s_waitcnt lgkmcnt(0)
	v_add_f32_e32 v232, v232, v22
	v_add_f32_e32 v233, v233, v23
	v_rcp_f32_e32 v232, v232
	v_rcp_f32_e32 v233, v233
	s_nop 0
	v_mul_f32_e32 v233, v24, v233
	v_mul_f32_e32 v128, v128, v233
	v_mul_f32_e32 v129, v129, v233
	v_mul_f32_e32 v130, v130, v233
	v_mul_f32_e32 v131, v131, v233
	v_mul_f32_e32 v132, v132, v233
	v_mul_f32_e32 v133, v133, v233
	v_mul_f32_e32 v134, v134, v233
	v_mul_f32_e32 v135, v135, v233
	v_mul_f32_e32 v136, v136, v233
	v_mul_f32_e32 v137, v137, v233
	v_mul_f32_e32 v138, v138, v233
	v_mul_f32_e32 v139, v139, v233
	v_mul_f32_e32 v140, v140, v233
	v_mul_f32_e32 v141, v141, v233
	v_mul_f32_e32 v142, v142, v233
	v_mul_f32_e32 v143, v143, v233
	v_mul_f32_e32 v144, v144, v233
	v_mul_f32_e32 v145, v145, v233
	v_mul_f32_e32 v146, v146, v233
	v_mul_f32_e32 v147, v147, v233
	v_mul_f32_e32 v148, v148, v233
	v_mul_f32_e32 v149, v149, v233
	v_mul_f32_e32 v150, v150, v233
	v_mul_f32_e32 v151, v151, v233
	v_mul_f32_e32 v152, v152, v233
	v_mul_f32_e32 v153, v153, v233
	v_mul_f32_e32 v154, v154, v233
	v_mul_f32_e32 v155, v155, v233
	v_mul_f32_e32 v156, v156, v233
	v_mul_f32_e32 v157, v157, v233
	v_mul_f32_e32 v158, v158, v233
	v_mul_f32_e32 v159, v159, v233
	v_mul_f32_e32 v160, v160, v233
	v_mul_f32_e32 v161, v161, v233
	v_mul_f32_e32 v162, v162, v233
	v_mul_f32_e32 v163, v163, v233
	v_mul_f32_e32 v164, v164, v233
	v_mul_f32_e32 v165, v165, v233
	v_mul_f32_e32 v166, v166, v233
	v_mul_f32_e32 v167, v167, v233
	v_mul_f32_e32 v168, v168, v233
	v_mul_f32_e32 v169, v169, v233
	v_mul_f32_e32 v170, v170, v233
	v_mul_f32_e32 v171, v171, v233
	v_mul_f32_e32 v172, v172, v233
	v_mul_f32_e32 v173, v173, v233
	v_mul_f32_e32 v174, v174, v233
	v_mul_f32_e32 v175, v175, v233
	v_mul_f32_e32 v176, v176, v233
	v_mul_f32_e32 v177, v177, v233
	v_mul_f32_e32 v178, v178, v233
	v_mul_f32_e32 v179, v179, v233
	v_mul_f32_e32 v180, v180, v233
	v_mul_f32_e32 v181, v181, v233
	v_mul_f32_e32 v182, v182, v233
	v_mul_f32_e32 v183, v183, v233
	v_mul_f32_e32 v184, v184, v233
	v_mul_f32_e32 v185, v185, v233
	v_mul_f32_e32 v186, v186, v233
	v_mul_f32_e32 v187, v187, v233
	v_mul_f32_e32 v188, v188, v233
	v_mul_f32_e32 v189, v189, v233
	v_mul_f32_e32 v190, v190, v233
	v_mul_f32_e32 v191, v191, v233
	v_fma_f32 v64, v64, v232, -v128
	v_fma_f32 v65, v65, v232, -v129
	v_fma_f32 v66, v66, v232, -v130
	v_fma_f32 v67, v67, v232, -v131
	v_fma_f32 v68, v68, v232, -v132
	v_fma_f32 v69, v69, v232, -v133
	v_fma_f32 v70, v70, v232, -v134
	v_fma_f32 v71, v71, v232, -v135
	v_fma_f32 v72, v72, v232, -v136
	v_fma_f32 v73, v73, v232, -v137
	v_fma_f32 v74, v74, v232, -v138
	v_fma_f32 v75, v75, v232, -v139
	v_fma_f32 v76, v76, v232, -v140
	v_fma_f32 v77, v77, v232, -v141
	v_fma_f32 v78, v78, v232, -v142
	v_fma_f32 v79, v79, v232, -v143
	v_fma_f32 v80, v80, v232, -v144
	v_fma_f32 v81, v81, v232, -v145
	v_fma_f32 v82, v82, v232, -v146
	v_fma_f32 v83, v83, v232, -v147
	v_fma_f32 v84, v84, v232, -v148
	v_fma_f32 v85, v85, v232, -v149
	v_fma_f32 v86, v86, v232, -v150
	v_fma_f32 v87, v87, v232, -v151
	v_fma_f32 v88, v88, v232, -v152
	v_fma_f32 v89, v89, v232, -v153
	v_fma_f32 v90, v90, v232, -v154
	v_fma_f32 v91, v91, v232, -v155
	v_fma_f32 v92, v92, v232, -v156
	v_fma_f32 v93, v93, v232, -v157
	v_fma_f32 v94, v94, v232, -v158
	v_fma_f32 v95, v95, v232, -v159
	v_fma_f32 v96, v96, v232, -v160
	v_fma_f32 v97, v97, v232, -v161
	v_fma_f32 v98, v98, v232, -v162
	v_fma_f32 v99, v99, v232, -v163
	v_fma_f32 v100, v100, v232, -v164
	v_fma_f32 v101, v101, v232, -v165
	v_fma_f32 v102, v102, v232, -v166
	v_fma_f32 v103, v103, v232, -v167
	v_fma_f32 v104, v104, v232, -v168
	v_fma_f32 v105, v105, v232, -v169
	v_fma_f32 v106, v106, v232, -v170
	v_fma_f32 v107, v107, v232, -v171
	v_fma_f32 v108, v108, v232, -v172
	v_fma_f32 v109, v109, v232, -v173
	v_fma_f32 v110, v110, v232, -v174
	v_fma_f32 v111, v111, v232, -v175
	v_fma_f32 v112, v112, v232, -v176
	v_fma_f32 v113, v113, v232, -v177
	v_fma_f32 v114, v114, v232, -v178
	v_fma_f32 v115, v115, v232, -v179
	v_fma_f32 v116, v116, v232, -v180
	v_fma_f32 v117, v117, v232, -v181
	v_fma_f32 v118, v118, v232, -v182
	v_fma_f32 v119, v119, v232, -v183
	v_fma_f32 v120, v120, v232, -v184
	v_fma_f32 v121, v121, v232, -v185
	v_fma_f32 v122, v122, v232, -v186
	v_fma_f32 v123, v123, v232, -v187
	v_fma_f32 v124, v124, v232, -v188
	v_fma_f32 v125, v125, v232, -v189
	v_fma_f32 v126, v126, v232, -v190
	v_fma_f32 v127, v127, v232, -v191
	v_mul_f32_e32 v234, v64, v64
	v_fmac_f32_e32 v234, v65, v65
	v_fmac_f32_e32 v234, v66, v66
	v_fmac_f32_e32 v234, v67, v67
	v_fmac_f32_e32 v234, v68, v68
	v_fmac_f32_e32 v234, v69, v69
	v_fmac_f32_e32 v234, v70, v70
	v_fmac_f32_e32 v234, v71, v71
	v_fmac_f32_e32 v234, v72, v72
	v_fmac_f32_e32 v234, v73, v73
	v_fmac_f32_e32 v234, v74, v74
	v_fmac_f32_e32 v234, v75, v75
	v_fmac_f32_e32 v234, v76, v76
	v_fmac_f32_e32 v234, v77, v77
	v_fmac_f32_e32 v234, v78, v78
	v_fmac_f32_e32 v234, v79, v79
	v_fmac_f32_e32 v234, v80, v80
	v_fmac_f32_e32 v234, v81, v81
	v_fmac_f32_e32 v234, v82, v82
	v_fmac_f32_e32 v234, v83, v83
	v_fmac_f32_e32 v234, v84, v84
	v_fmac_f32_e32 v234, v85, v85
	v_fmac_f32_e32 v234, v86, v86
	v_fmac_f32_e32 v234, v87, v87
	v_fmac_f32_e32 v234, v88, v88
	v_fmac_f32_e32 v234, v89, v89
	v_fmac_f32_e32 v234, v90, v90
	v_fmac_f32_e32 v234, v91, v91
	v_fmac_f32_e32 v234, v92, v92
	v_fmac_f32_e32 v234, v93, v93
	v_fmac_f32_e32 v234, v94, v94
	v_fmac_f32_e32 v234, v95, v95
	v_fmac_f32_e32 v234, v96, v96
	v_fmac_f32_e32 v234, v97, v97
	v_fmac_f32_e32 v234, v98, v98
	v_fmac_f32_e32 v234, v99, v99
	v_fmac_f32_e32 v234, v100, v100
	v_fmac_f32_e32 v234, v101, v101
	v_fmac_f32_e32 v234, v102, v102
	v_fmac_f32_e32 v234, v103, v103
	v_fmac_f32_e32 v234, v104, v104
	v_fmac_f32_e32 v234, v105, v105
	v_fmac_f32_e32 v234, v106, v106
	v_fmac_f32_e32 v234, v107, v107
	v_fmac_f32_e32 v234, v108, v108
	v_fmac_f32_e32 v234, v109, v109
	v_fmac_f32_e32 v234, v110, v110
	v_fmac_f32_e32 v234, v111, v111
	v_fmac_f32_e32 v234, v112, v112
	v_fmac_f32_e32 v234, v113, v113
	v_fmac_f32_e32 v234, v114, v114
	v_fmac_f32_e32 v234, v115, v115
	v_fmac_f32_e32 v234, v116, v116
	v_fmac_f32_e32 v234, v117, v117
	v_fmac_f32_e32 v234, v118, v118
	v_fmac_f32_e32 v234, v119, v119
	v_fmac_f32_e32 v234, v120, v120
	v_fmac_f32_e32 v234, v121, v121
	v_fmac_f32_e32 v234, v122, v122
	v_fmac_f32_e32 v234, v123, v123
	v_fmac_f32_e32 v234, v124, v124
	v_fmac_f32_e32 v234, v125, v125
	v_fmac_f32_e32 v234, v126, v126
	v_fmac_f32_e32 v234, v127, v127
	ds_bpermute_b32 v235, v26, v234
	s_waitcnt lgkmcnt(0)
	v_add_f32_e32 v234, v234, v235
	v_mov_b32_e32 v235, 0x3727c5ac
	v_fmamk_f32 v234, v234, 0x3c000000, v235
	v_rsq_f32_e32 v234, v234
	s_nop 0
	v_mul_f32_e32 v234, s12, v234
	s_lshl_b32 s20, s19, 11
	s_lshl_b32 s21, s14, 8
	s_add_u32 s20, s20, s21
	s_add_u32 s76, s92, 0x22100000
	s_addc_u32 s77, s93, 0
	s_add_u32 s76, s76, s20
	s_addc_u32 s77, s77, 0
	v_lshlrev_b32_e32 v28, 11, v30
	v_lshl_add_u32 v28, v2, 3, v28
	v_accvgpr_read_b32 v236, a128
	v_accvgpr_read_b32 v237, a129
	v_accvgpr_read_b32 v238, a130
	v_accvgpr_read_b32 v239, a131
	v_mul_f32_e32 v64, v64, v234
	v_mul_f32_e32 v65, v65, v234
	v_mul_f32_e32 v66, v66, v234
	v_mul_f32_e32 v67, v67, v234
	v_mul_f32_e32 v64, v64, v236
	v_mul_f32_e32 v65, v65, v237
	v_mul_f32_e32 v66, v66, v238
	v_mul_f32_e32 v67, v67, v239
	v_cvt_pk_bf16_f32 v240, v64, v65
	v_cvt_pk_bf16_f32 v241, v66, v67
	global_store_dwordx2 v28, v[240:241], s[76:77] offset:0
	v_accvgpr_read_b32 v236, a132
	v_accvgpr_read_b32 v237, a133
	v_accvgpr_read_b32 v238, a134
	v_accvgpr_read_b32 v239, a135
	v_mul_f32_e32 v68, v68, v234
	v_mul_f32_e32 v69, v69, v234
	v_mul_f32_e32 v70, v70, v234
	v_mul_f32_e32 v71, v71, v234
	v_mul_f32_e32 v68, v68, v236
	v_mul_f32_e32 v69, v69, v237
	v_mul_f32_e32 v70, v70, v238
	v_mul_f32_e32 v71, v71, v239
	v_cvt_pk_bf16_f32 v240, v68, v69
	v_cvt_pk_bf16_f32 v241, v70, v71
	global_store_dwordx2 v28, v[240:241], s[76:77] offset:16
	v_accvgpr_read_b32 v236, a136
	v_accvgpr_read_b32 v237, a137
	v_accvgpr_read_b32 v238, a138
	v_accvgpr_read_b32 v239, a139
	v_mul_f32_e32 v72, v72, v234
	v_mul_f32_e32 v73, v73, v234
	v_mul_f32_e32 v74, v74, v234
	v_mul_f32_e32 v75, v75, v234
	v_mul_f32_e32 v72, v72, v236
	v_mul_f32_e32 v73, v73, v237
	v_mul_f32_e32 v74, v74, v238
	v_mul_f32_e32 v75, v75, v239
	v_cvt_pk_bf16_f32 v240, v72, v73
	v_cvt_pk_bf16_f32 v241, v74, v75
	global_store_dwordx2 v28, v[240:241], s[76:77] offset:32
	v_accvgpr_read_b32 v236, a140
	v_accvgpr_read_b32 v237, a141
	v_accvgpr_read_b32 v238, a142
	v_accvgpr_read_b32 v239, a143
	v_mul_f32_e32 v76, v76, v234
	v_mul_f32_e32 v77, v77, v234
	v_mul_f32_e32 v78, v78, v234
	v_mul_f32_e32 v79, v79, v234
	v_mul_f32_e32 v76, v76, v236
	v_mul_f32_e32 v77, v77, v237
	v_mul_f32_e32 v78, v78, v238
	v_mul_f32_e32 v79, v79, v239
	v_cvt_pk_bf16_f32 v240, v76, v77
	v_cvt_pk_bf16_f32 v241, v78, v79
	global_store_dwordx2 v28, v[240:241], s[76:77] offset:48
	v_accvgpr_read_b32 v236, a144
	v_accvgpr_read_b32 v237, a145
	v_accvgpr_read_b32 v238, a146
	v_accvgpr_read_b32 v239, a147
	v_mul_f32_e32 v80, v80, v234
	v_mul_f32_e32 v81, v81, v234
	v_mul_f32_e32 v82, v82, v234
	v_mul_f32_e32 v83, v83, v234
	v_mul_f32_e32 v80, v80, v236
	v_mul_f32_e32 v81, v81, v237
	v_mul_f32_e32 v82, v82, v238
	v_mul_f32_e32 v83, v83, v239
	v_cvt_pk_bf16_f32 v240, v80, v81
	v_cvt_pk_bf16_f32 v241, v82, v83
	global_store_dwordx2 v28, v[240:241], s[76:77] offset:64
	v_accvgpr_read_b32 v236, a148
	v_accvgpr_read_b32 v237, a149
	v_accvgpr_read_b32 v238, a150
	v_accvgpr_read_b32 v239, a151
	v_mul_f32_e32 v84, v84, v234
	v_mul_f32_e32 v85, v85, v234
	v_mul_f32_e32 v86, v86, v234
	v_mul_f32_e32 v87, v87, v234
	v_mul_f32_e32 v84, v84, v236
	v_mul_f32_e32 v85, v85, v237
	v_mul_f32_e32 v86, v86, v238
	v_mul_f32_e32 v87, v87, v239
	v_cvt_pk_bf16_f32 v240, v84, v85
	v_cvt_pk_bf16_f32 v241, v86, v87
	global_store_dwordx2 v28, v[240:241], s[76:77] offset:80
	v_accvgpr_read_b32 v236, a152
	v_accvgpr_read_b32 v237, a153
	v_accvgpr_read_b32 v238, a154
	v_accvgpr_read_b32 v239, a155
	v_mul_f32_e32 v88, v88, v234
	v_mul_f32_e32 v89, v89, v234
	v_mul_f32_e32 v90, v90, v234
	v_mul_f32_e32 v91, v91, v234
	v_mul_f32_e32 v88, v88, v236
	v_mul_f32_e32 v89, v89, v237
	v_mul_f32_e32 v90, v90, v238
	v_mul_f32_e32 v91, v91, v239
	v_cvt_pk_bf16_f32 v240, v88, v89
	v_cvt_pk_bf16_f32 v241, v90, v91
	global_store_dwordx2 v28, v[240:241], s[76:77] offset:96
	v_accvgpr_read_b32 v236, a156
	v_accvgpr_read_b32 v237, a157
	v_accvgpr_read_b32 v238, a158
	v_accvgpr_read_b32 v239, a159
	v_mul_f32_e32 v92, v92, v234
	v_mul_f32_e32 v93, v93, v234
	v_mul_f32_e32 v94, v94, v234
	v_mul_f32_e32 v95, v95, v234
	v_mul_f32_e32 v92, v92, v236
	v_mul_f32_e32 v93, v93, v237
	v_mul_f32_e32 v94, v94, v238
	v_mul_f32_e32 v95, v95, v239
	v_cvt_pk_bf16_f32 v240, v92, v93
	v_cvt_pk_bf16_f32 v241, v94, v95
	global_store_dwordx2 v28, v[240:241], s[76:77] offset:112
	v_accvgpr_read_b32 v236, a160
	v_accvgpr_read_b32 v237, a161
	v_accvgpr_read_b32 v238, a162
	v_accvgpr_read_b32 v239, a163
	v_mul_f32_e32 v96, v96, v234
	v_mul_f32_e32 v97, v97, v234
	v_mul_f32_e32 v98, v98, v234
	v_mul_f32_e32 v99, v99, v234
	v_mul_f32_e32 v96, v96, v236
	v_mul_f32_e32 v97, v97, v237
	v_mul_f32_e32 v98, v98, v238
	v_mul_f32_e32 v99, v99, v239
	v_cvt_pk_bf16_f32 v240, v96, v97
	v_cvt_pk_bf16_f32 v241, v98, v99
	global_store_dwordx2 v28, v[240:241], s[76:77] offset:128
	v_accvgpr_read_b32 v236, a164
	v_accvgpr_read_b32 v237, a165
	v_accvgpr_read_b32 v238, a166
	v_accvgpr_read_b32 v239, a167
	v_mul_f32_e32 v100, v100, v234
	v_mul_f32_e32 v101, v101, v234
	v_mul_f32_e32 v102, v102, v234
	v_mul_f32_e32 v103, v103, v234
	v_mul_f32_e32 v100, v100, v236
	v_mul_f32_e32 v101, v101, v237
	v_mul_f32_e32 v102, v102, v238
	v_mul_f32_e32 v103, v103, v239
	v_cvt_pk_bf16_f32 v240, v100, v101
	v_cvt_pk_bf16_f32 v241, v102, v103
	global_store_dwordx2 v28, v[240:241], s[76:77] offset:144
	v_accvgpr_read_b32 v236, a168
	v_accvgpr_read_b32 v237, a169
	v_accvgpr_read_b32 v238, a170
	v_accvgpr_read_b32 v239, a171
	v_mul_f32_e32 v104, v104, v234
	v_mul_f32_e32 v105, v105, v234
	v_mul_f32_e32 v106, v106, v234
	v_mul_f32_e32 v107, v107, v234
	v_mul_f32_e32 v104, v104, v236
	v_mul_f32_e32 v105, v105, v237
	v_mul_f32_e32 v106, v106, v238
	v_mul_f32_e32 v107, v107, v239
	v_cvt_pk_bf16_f32 v240, v104, v105
	v_cvt_pk_bf16_f32 v241, v106, v107
	global_store_dwordx2 v28, v[240:241], s[76:77] offset:160
	v_accvgpr_read_b32 v236, a172
	v_accvgpr_read_b32 v237, a173
	v_accvgpr_read_b32 v238, a174
	v_accvgpr_read_b32 v239, a175
	v_mul_f32_e32 v108, v108, v234
	v_mul_f32_e32 v109, v109, v234
	v_mul_f32_e32 v110, v110, v234
	v_mul_f32_e32 v111, v111, v234
	v_mul_f32_e32 v108, v108, v236
	v_mul_f32_e32 v109, v109, v237
	v_mul_f32_e32 v110, v110, v238
	v_mul_f32_e32 v111, v111, v239
	v_cvt_pk_bf16_f32 v240, v108, v109
	v_cvt_pk_bf16_f32 v241, v110, v111
	global_store_dwordx2 v28, v[240:241], s[76:77] offset:176
	v_accvgpr_read_b32 v236, a176
	v_accvgpr_read_b32 v237, a177
	v_accvgpr_read_b32 v238, a178
	v_accvgpr_read_b32 v239, a179
	v_mul_f32_e32 v112, v112, v234
	v_mul_f32_e32 v113, v113, v234
	v_mul_f32_e32 v114, v114, v234
	v_mul_f32_e32 v115, v115, v234
	v_mul_f32_e32 v112, v112, v236
	v_mul_f32_e32 v113, v113, v237
	v_mul_f32_e32 v114, v114, v238
	v_mul_f32_e32 v115, v115, v239
	v_cvt_pk_bf16_f32 v240, v112, v113
	v_cvt_pk_bf16_f32 v241, v114, v115
	global_store_dwordx2 v28, v[240:241], s[76:77] offset:192
	v_accvgpr_read_b32 v236, a180
	v_accvgpr_read_b32 v237, a181
	v_accvgpr_read_b32 v238, a182
	v_accvgpr_read_b32 v239, a183
	v_mul_f32_e32 v116, v116, v234
	v_mul_f32_e32 v117, v117, v234
	v_mul_f32_e32 v118, v118, v234
	v_mul_f32_e32 v119, v119, v234
	v_mul_f32_e32 v116, v116, v236
	v_mul_f32_e32 v117, v117, v237
	v_mul_f32_e32 v118, v118, v238
	v_mul_f32_e32 v119, v119, v239
	v_cvt_pk_bf16_f32 v240, v116, v117
	v_cvt_pk_bf16_f32 v241, v118, v119
	global_store_dwordx2 v28, v[240:241], s[76:77] offset:208
	v_accvgpr_read_b32 v236, a184
	v_accvgpr_read_b32 v237, a185
	v_accvgpr_read_b32 v238, a186
	v_accvgpr_read_b32 v239, a187
	v_mul_f32_e32 v120, v120, v234
	v_mul_f32_e32 v121, v121, v234
	v_mul_f32_e32 v122, v122, v234
	v_mul_f32_e32 v123, v123, v234
	v_mul_f32_e32 v120, v120, v236
	v_mul_f32_e32 v121, v121, v237
	v_mul_f32_e32 v122, v122, v238
	v_mul_f32_e32 v123, v123, v239
	v_cvt_pk_bf16_f32 v240, v120, v121
	v_cvt_pk_bf16_f32 v241, v122, v123
	global_store_dwordx2 v28, v[240:241], s[76:77] offset:224
	v_accvgpr_read_b32 v236, a188
	v_accvgpr_read_b32 v237, a189
	v_accvgpr_read_b32 v238, a190
	v_accvgpr_read_b32 v239, a191
	v_mul_f32_e32 v124, v124, v234
	v_mul_f32_e32 v125, v125, v234
	v_mul_f32_e32 v126, v126, v234
	v_mul_f32_e32 v127, v127, v234
	v_mul_f32_e32 v124, v124, v236
	v_mul_f32_e32 v125, v125, v237
	v_mul_f32_e32 v126, v126, v238
	v_mul_f32_e32 v127, v127, v239
	v_cvt_pk_bf16_f32 v240, v124, v125
	v_cvt_pk_bf16_f32 v241, v126, v127
	global_store_dwordx2 v28, v[240:241], s[76:77] offset:240
	s_add_u32 s22, s22, s8
	s_cmp_lt_u32 s22, 0x800
	s_cbranch_scc1 .Lat_item
.Lat_done:
	s_waitcnt vmcnt(0) lgkmcnt(0)
	s_or_b64 exec, exec, s[82:83]
